# grid barrier: non-leader workgroups issue their cache invalidate right after arriving (waves parked, polls bypass L1) instead of after the release
# speedup vs baseline: 1.0427x; 1.0106x over previous
; __device__ __forceinline__ unsigned xb_ld(unsigned* p)              { return __hip_atomic_load(p, __ATOMIC_RELAXED, __HIP_MEMORY_SCOPE_AGENT); }
; __device__ __forceinline__ unsigned xb_add(unsigned* p, unsigned v) { return __hip_atomic_fetch_add(p, v, __ATOMIC_RELAXED, __HIP_MEMORY_SCOPE_AGENT); }
; #define XB_SPIN(cond, bar) do { unsigned _sp = 0; while (cond) { __builtin_amdgcn_s_sleep(1); \
;     if ((++_sp & 255u) == 0u) { if (xb_ld(&(bar)[XB_TMO])) break; if (_sp > XB_SPIN_CAP) { atomicAdd(&(bar)[XB_TMO], 1u); break; } } } } while (0)
; __device__ __forceinline__ void xcd_barrier(const XcdBarrier& b) {
;     ...
;     if (threadIdx.x == 0) {
;         unsigned* bar = b.bar;
;         __builtin_amdgcn_s_waitcnt(0);
;         unsigned nloc = b.st[0], nx = b.st[1];
;         if (nloc == 0u) { xcd_barrier_complete(bar, b.x, nloc, nx); b.st[0] = nloc; b.st[1] = nx; }
;         const unsigned old = xb_add(&bar[XB_XSUB(b.x)], 1u);
;         const unsigned gen = old / nloc;
;         if (old + 1u == (gen + 1u) * nloc) {
;             __builtin_amdgcn_fence(__ATOMIC_RELEASE, "agent");
;             asm volatile("s_waitcnt vmcnt(0)" ::: "memory");
;             const unsigned og = xb_add(&bar[XB_TOP], 1u);
;             const unsigned tg = og / nx;
;             if (og + 1u == (tg + 1u) * nx) xb_add(&bar[XB_TOPGEN], 1u);
;             else XB_SPIN(xb_ld(&bar[XB_TOPGEN]) == tg, bar);
;             __builtin_amdgcn_fence(__ATOMIC_ACQUIRE, "agent");
;             xb_add(&bar[XB_XGEN(b.x)], 1u);
;             asm volatile("s_waitcnt vmcnt(0)" ::: "memory");
;         } else {
;             XB_SPIN(xb_ld(&bar[XB_XGEN(b.x)]) == gen, bar);
.LBB0_93:
	s_or_b64 exec, exec, s[14:15]
	buffer_inv sc1
	v_cvt_f32_u32_e32 v5, v3
	s_waitcnt vmcnt(1)
	v_readfirstlane_b32 s3, v4
	v_sub_u32_e32 v4, 0, v3
	v_rcp_iflag_f32_e32 v5, v5
	v_add_u32_e32 v6, s3, v2
	v_mul_f32_e32 v5, 0x4f7ffffe, v5
	v_cvt_u32_f32_e32 v5, v5
	v_mul_lo_u32 v2, v4, v5
	v_mul_hi_u32 v2, v5, v2
	v_add_u32_e32 v2, v5, v2
	v_mul_hi_u32 v2, v6, v2
	v_mul_lo_u32 v4, v2, v3
	v_sub_u32_e32 v4, v6, v4
	v_add_u32_e32 v5, 1, v2
	v_cmp_ge_u32_e32 vcc, v4, v3
	s_nop 1
	v_cndmask_b32_e32 v2, v2, v5, vcc
	v_sub_u32_e32 v5, v4, v3
	v_cndmask_b32_e32 v4, v4, v5, vcc
	v_add_u32_e32 v5, 1, v2
	v_cmp_ge_u32_e32 vcc, v4, v3
	v_add_u32_e32 v4, 1, v6
	s_nop 0
	v_cndmask_b32_e32 v2, v2, v5, vcc
	v_mul_lo_u32 v5, v3, v2
	v_add_u32_e32 v3, v5, v3
	v_cmp_ne_u32_e32 vcc, v4, v3
	s_and_saveexec_b64 s[8:9], vcc
	s_xor_b64 s[8:9], exec, s[8:9]
	s_cbranch_execz .LBB0_107
	s_waitcnt lgkmcnt(0)
	v_mov_b32_e32 v1, 0x2000
	global_load_dword v1, v1, s[6:7] offset:1024 sc1
	s_add_u32 s20, s6, 0x2400
	s_addc_u32 s21, s7, 0
	s_waitcnt vmcnt(0)
	v_cmp_eq_u32_e32 vcc, v1, v2
	s_and_saveexec_b64 s[14:15], vcc
	s_cbranch_execz .LBB0_106
	s_add_u32 s16, s30, 0x1200
	s_addc_u32 s17, s31, 0
	s_mov_b32 s3, 1
	s_mov_b64 s[38:39], 0
	v_mov_b32_e32 v1, 0
	s_branch .LBB0_97

; __device__ __forceinline__ unsigned xb_ld(unsigned* p)              { return __hip_atomic_load(p, __ATOMIC_RELAXED, __HIP_MEMORY_SCOPE_AGENT); }
; #define XB_SPIN(cond, bar) do { unsigned _sp = 0; while (cond) { __builtin_amdgcn_s_sleep(1); \
;     if ((++_sp & 255u) == 0u) { if (xb_ld(&(bar)[XB_TMO])) break; if (_sp > XB_SPIN_CAP) { atomicAdd(&(bar)[XB_TMO], 1u); break; } } } } while (0)
; __device__ __forceinline__ void xcd_barrier(const XcdBarrier& b) {
;     ...
;         } else {
;             XB_SPIN(xb_ld(&bar[XB_XGEN(b.x)]) == gen, bar);
;             __builtin_amdgcn_fence(__ATOMIC_ACQUIRE, "agent");
;             asm volatile("s_waitcnt vmcnt(0)" ::: "memory");
.LBB0_106:
	s_or_b64 exec, exec, s[14:15]
	s_waitcnt vmcnt(0)
	s_waitcnt vmcnt(0)

; __device__ __forceinline__ unsigned xb_ld(unsigned* p)              { return __hip_atomic_load(p, __ATOMIC_RELAXED, __HIP_MEMORY_SCOPE_AGENT); }
; __device__ __forceinline__ unsigned xb_add(unsigned* p, unsigned v) { return __hip_atomic_fetch_add(p, v, __ATOMIC_RELAXED, __HIP_MEMORY_SCOPE_AGENT); }
; #define XB_SPIN(cond, bar) do { unsigned _sp = 0; while (cond) { __builtin_amdgcn_s_sleep(1); \
;     if ((++_sp & 255u) == 0u) { if (xb_ld(&(bar)[XB_TMO])) break; if (_sp > XB_SPIN_CAP) { atomicAdd(&(bar)[XB_TMO], 1u); break; } } } } while (0)
; __device__ __forceinline__ void xcd_barrier(const XcdBarrier& b) {
;     ...
;     if (threadIdx.x == 0) {
;         unsigned* bar = b.bar;
;         __builtin_amdgcn_s_waitcnt(0);
;         unsigned nloc = b.st[0], nx = b.st[1];
;         if (nloc == 0u) { xcd_barrier_complete(bar, b.x, nloc, nx); b.st[0] = nloc; b.st[1] = nx; }
;         const unsigned old = xb_add(&bar[XB_XSUB(b.x)], 1u);
;         const unsigned gen = old / nloc;
;         if (old + 1u == (gen + 1u) * nloc) {
;             __builtin_amdgcn_fence(__ATOMIC_RELEASE, "agent");
;             asm volatile("s_waitcnt vmcnt(0)" ::: "memory");
;             const unsigned og = xb_add(&bar[XB_TOP], 1u);
;             const unsigned tg = og / nx;
;             if (og + 1u == (tg + 1u) * nx) xb_add(&bar[XB_TOPGEN], 1u);
;             else XB_SPIN(xb_ld(&bar[XB_TOPGEN]) == tg, bar);
;             __builtin_amdgcn_fence(__ATOMIC_ACQUIRE, "agent");
;             xb_add(&bar[XB_XGEN(b.x)], 1u);
;             asm volatile("s_waitcnt vmcnt(0)" ::: "memory");
;         } else {
;             XB_SPIN(xb_ld(&bar[XB_XGEN(b.x)]) == gen, bar);
.LBB0_491:
	s_or_b64 exec, exec, s[10:11]
	buffer_inv sc1
	v_cvt_f32_u32_e32 v5, v3
	s_waitcnt vmcnt(1)
	v_readfirstlane_b32 s3, v4
	v_sub_u32_e32 v4, 0, v3
	v_rcp_iflag_f32_e32 v5, v5
	v_add_u32_e32 v6, s3, v2
	v_mul_f32_e32 v5, 0x4f7ffffe, v5
	v_cvt_u32_f32_e32 v5, v5
	v_mul_lo_u32 v2, v4, v5
	v_mul_hi_u32 v2, v5, v2
	v_add_u32_e32 v2, v5, v2
	v_mul_hi_u32 v2, v6, v2
	v_mul_lo_u32 v4, v2, v3
	v_sub_u32_e32 v4, v6, v4
	v_add_u32_e32 v5, 1, v2
	v_cmp_ge_u32_e32 vcc, v4, v3
	s_nop 1
	v_cndmask_b32_e32 v2, v2, v5, vcc
	v_sub_u32_e32 v5, v4, v3
	v_cndmask_b32_e32 v4, v4, v5, vcc
	v_add_u32_e32 v5, 1, v2
	v_cmp_ge_u32_e32 vcc, v4, v3
	v_add_u32_e32 v4, 1, v6
	s_nop 0
	v_cndmask_b32_e32 v2, v2, v5, vcc
	v_mul_lo_u32 v5, v3, v2
	v_add_u32_e32 v3, v5, v3
	v_cmp_ne_u32_e32 vcc, v4, v3
	s_and_saveexec_b64 s[8:9], vcc
	s_xor_b64 s[8:9], exec, s[8:9]
	s_cbranch_execz .LBB0_505
	s_waitcnt lgkmcnt(0)
	v_mov_b32_e32 v1, 0x2000
	global_load_dword v1, v1, s[6:7] offset:1024 sc1
	s_add_u32 s14, s6, 0x2400
	s_addc_u32 s15, s7, 0
	s_waitcnt vmcnt(0)
	v_cmp_eq_u32_e32 vcc, v1, v2
	s_and_saveexec_b64 s[10:11], vcc
	s_cbranch_execz .LBB0_504
	s_add_u32 s12, s30, 0x1200
	s_addc_u32 s13, s31, 0
	s_mov_b32 s3, 1
	s_mov_b64 s[16:17], 0
	v_mov_b32_e32 v1, 0
	s_branch .LBB0_495

; __device__ __forceinline__ unsigned xb_ld(unsigned* p)              { return __hip_atomic_load(p, __ATOMIC_RELAXED, __HIP_MEMORY_SCOPE_AGENT); }
; #define XB_SPIN(cond, bar) do { unsigned _sp = 0; while (cond) { __builtin_amdgcn_s_sleep(1); \
;     if ((++_sp & 255u) == 0u) { if (xb_ld(&(bar)[XB_TMO])) break; if (_sp > XB_SPIN_CAP) { atomicAdd(&(bar)[XB_TMO], 1u); break; } } } } while (0)
; __device__ __forceinline__ void xcd_barrier(const XcdBarrier& b) {
;     ...
;         } else {
;             XB_SPIN(xb_ld(&bar[XB_XGEN(b.x)]) == gen, bar);
;             __builtin_amdgcn_fence(__ATOMIC_ACQUIRE, "agent");
;             asm volatile("s_waitcnt vmcnt(0)" ::: "memory");
.LBB0_504:
	s_or_b64 exec, exec, s[10:11]
	s_waitcnt vmcnt(0)
	s_waitcnt vmcnt(0)

; __device__ __forceinline__ unsigned xb_ld(unsigned* p)              { return __hip_atomic_load(p, __ATOMIC_RELAXED, __HIP_MEMORY_SCOPE_AGENT); }
; __device__ __forceinline__ unsigned xb_add(unsigned* p, unsigned v) { return __hip_atomic_fetch_add(p, v, __ATOMIC_RELAXED, __HIP_MEMORY_SCOPE_AGENT); }
; #define XB_SPIN(cond, bar) do { unsigned _sp = 0; while (cond) { __builtin_amdgcn_s_sleep(1); \
;     if ((++_sp & 255u) == 0u) { if (xb_ld(&(bar)[XB_TMO])) break; if (_sp > XB_SPIN_CAP) { atomicAdd(&(bar)[XB_TMO], 1u); break; } } } } while (0)
; __device__ __forceinline__ void xcd_barrier(const XcdBarrier& b) {
;     ...
;     if (threadIdx.x == 0) {
;         unsigned* bar = b.bar;
;         __builtin_amdgcn_s_waitcnt(0);
;         unsigned nloc = b.st[0], nx = b.st[1];
;         if (nloc == 0u) { xcd_barrier_complete(bar, b.x, nloc, nx); b.st[0] = nloc; b.st[1] = nx; }
;         const unsigned old = xb_add(&bar[XB_XSUB(b.x)], 1u);
;         const unsigned gen = old / nloc;
;         if (old + 1u == (gen + 1u) * nloc) {
;             __builtin_amdgcn_fence(__ATOMIC_RELEASE, "agent");
;             asm volatile("s_waitcnt vmcnt(0)" ::: "memory");
;             const unsigned og = xb_add(&bar[XB_TOP], 1u);
;             const unsigned tg = og / nx;
;             if (og + 1u == (tg + 1u) * nx) xb_add(&bar[XB_TOPGEN], 1u);
;             else XB_SPIN(xb_ld(&bar[XB_TOPGEN]) == tg, bar);
;             __builtin_amdgcn_fence(__ATOMIC_ACQUIRE, "agent");
;             xb_add(&bar[XB_XGEN(b.x)], 1u);
;             asm volatile("s_waitcnt vmcnt(0)" ::: "memory");
;         } else {
;             XB_SPIN(xb_ld(&bar[XB_XGEN(b.x)]) == gen, bar);
.LBB0_833:
	s_or_b64 exec, exec, s[8:9]
	buffer_inv sc1
	v_cvt_f32_u32_e32 v5, v3
	s_waitcnt vmcnt(1)
	v_readfirstlane_b32 s3, v4
	v_sub_u32_e32 v4, 0, v3
	v_rcp_iflag_f32_e32 v5, v5
	v_add_u32_e32 v6, s3, v2
	v_mul_f32_e32 v5, 0x4f7ffffe, v5
	v_cvt_u32_f32_e32 v5, v5
	v_mul_lo_u32 v2, v4, v5
	v_mul_hi_u32 v2, v5, v2
	v_add_u32_e32 v2, v5, v2
	v_mul_hi_u32 v2, v6, v2
	v_mul_lo_u32 v4, v2, v3
	v_sub_u32_e32 v4, v6, v4
	v_add_u32_e32 v5, 1, v2
	v_cmp_ge_u32_e32 vcc, v4, v3
	s_nop 1
	v_cndmask_b32_e32 v2, v2, v5, vcc
	v_sub_u32_e32 v5, v4, v3
	v_cndmask_b32_e32 v4, v4, v5, vcc
	v_add_u32_e32 v5, 1, v2
	v_cmp_ge_u32_e32 vcc, v4, v3
	v_add_u32_e32 v4, 1, v6
	s_nop 0
	v_cndmask_b32_e32 v2, v2, v5, vcc
	v_mul_lo_u32 v5, v3, v2
	v_add_u32_e32 v3, v5, v3
	v_cmp_ne_u32_e32 vcc, v4, v3
	s_and_saveexec_b64 s[6:7], vcc
	s_xor_b64 s[6:7], exec, s[6:7]
	s_cbranch_execz .LBB0_847
	s_waitcnt lgkmcnt(0)
	v_mov_b32_e32 v1, 0x2000
	global_load_dword v1, v1, s[4:5] offset:1024 sc1
	s_add_u32 s12, s4, 0x2400
	s_addc_u32 s13, s5, 0
	s_waitcnt vmcnt(0)
	v_cmp_eq_u32_e32 vcc, v1, v2
	s_and_saveexec_b64 s[8:9], vcc
	s_cbranch_execz .LBB0_846
	s_add_u32 s10, s30, 0x1200
	s_addc_u32 s11, s31, 0
	s_mov_b32 s3, 1
	s_mov_b64 s[14:15], 0
	v_mov_b32_e32 v1, 0
	s_branch .LBB0_837

; __device__ __forceinline__ unsigned xb_ld(unsigned* p)              { return __hip_atomic_load(p, __ATOMIC_RELAXED, __HIP_MEMORY_SCOPE_AGENT); }
; #define XB_SPIN(cond, bar) do { unsigned _sp = 0; while (cond) { __builtin_amdgcn_s_sleep(1); \
;     if ((++_sp & 255u) == 0u) { if (xb_ld(&(bar)[XB_TMO])) break; if (_sp > XB_SPIN_CAP) { atomicAdd(&(bar)[XB_TMO], 1u); break; } } } } while (0)
; __device__ __forceinline__ void xcd_barrier(const XcdBarrier& b) {
;     ...
;         } else {
;             XB_SPIN(xb_ld(&bar[XB_XGEN(b.x)]) == gen, bar);
;             __builtin_amdgcn_fence(__ATOMIC_ACQUIRE, "agent");
;             asm volatile("s_waitcnt vmcnt(0)" ::: "memory");
.LBB0_846:
	s_or_b64 exec, exec, s[8:9]
	s_waitcnt vmcnt(0)
	s_waitcnt vmcnt(0)
